# K-tile LDS-DMA issued before the V register load; end-of-iteration wait relaxed to vmcnt(1) (only the DMA must land before the barrier), V load waited at next iteration top
# baseline (speedup 1.0000x reference)
.LBB0_740:
	s_waitcnt vmcnt(0)
	v_mov_b64_e32 v[116:117], v[128:129]
	v_mov_b64_e32 v[118:119], v[130:131]

.Lkdma_done_l:
	global_load_dwordx4 v[128:131], v[172:173], off
	s_cmp_gt_i32 s67, s66
	s_cbranch_scc1 .Latt_wonly
	s_mul_i32 s50, s68, 0x3400
	v_add_u32_e32 v52, s50, v189
	ds_read_b128 v[48:51], v52
	ds_read_b128 v[132:135], v52 offset:32
	ds_read_b128 v[136:139], v52 offset:6656
	ds_read_b128 v[140:143], v52 offset:6688
	ds_read_b128 v[144:147], v52 offset:64
	ds_read_b128 v[148:151], v52 offset:96
	ds_read_b128 v[152:155], v52 offset:6720
	ds_read_b128 v[156:159], v52 offset:6752
	ds_read_b128 v[160:163], v52 offset:128
	ds_read_b128 v[192:195], v52 offset:160
	ds_read_b128 v[196:199], v52 offset:6784
	ds_read_b128 v[200:203], v52 offset:6816
	s_waitcnt lgkmcnt(11)
	v_mfma_f32_32x32x16_bf16 v[64:79], v[48:51], v[104:107], v[32:47]
	s_mul_i32 s50, s68, 0x2400
	s_waitcnt lgkmcnt(9)
	v_mfma_f32_32x32x16_bf16 v[48:63], v[136:139], v[104:107], v[32:47]
	v_mfma_f32_32x32x16_bf16 v[64:79], v[132:135], v[100:103], v[64:79]
	v_add_u32_e32 v132, s50, v165
	v_add_u32_e32 v133, 0x6800, v132
	v_add_u32_e32 v132, 0x7800, v132
	s_waitcnt lgkmcnt(8)
	v_mfma_f32_32x32x16_bf16 v[48:63], v[140:143], v[100:103], v[48:63]
	s_waitcnt lgkmcnt(7)
	v_mfma_f32_32x32x16_bf16 v[64:79], v[144:147], v[96:99], v[64:79]
	s_waitcnt lgkmcnt(5)
	v_mfma_f32_32x32x16_bf16 v[48:63], v[152:155], v[96:99], v[48:63]
	ds_read_b128 v[152:155], v133 offset:32
	v_mfma_f32_32x32x16_bf16 v[64:79], v[148:151], v[92:95], v[64:79]
	s_waitcnt lgkmcnt(5)
	v_mfma_f32_32x32x16_bf16 v[48:63], v[156:159], v[92:95], v[48:63]
	s_waitcnt lgkmcnt(4)
	v_mfma_f32_32x32x16_bf16 v[64:79], v[160:163], v[88:91], v[64:79]
	ds_read_b128 v[160:163], v133
	ds_read_b128 v[156:159], v132 offset:512
	ds_read_b128 v[148:151], v132 offset:544
	ds_read_b128 v[144:147], v133 offset:64
	ds_read_b128 v[140:143], v132 offset:576
	ds_read_b128 v[136:139], v133 offset:96
	ds_read_b128 v[132:135], v132 offset:608
	s_waitcnt lgkmcnt(9)
	v_mfma_f32_32x32x16_bf16 v[48:63], v[196:199], v[88:91], v[48:63]
	v_mfma_f32_32x32x16_bf16 v[64:79], v[192:195], v[84:87], v[64:79]
	s_waitcnt lgkmcnt(8)
	v_mfma_f32_32x32x16_bf16 v[48:63], v[200:203], v[84:87], v[48:63]
	s_xor_b32 s68, s68, 1
	s_mulk_i32 s68, 0x2400
	v_add_u32_e32 v191, s68, v188
	v_lshl_add_u64 v[172:173], v[172:173], 0, s[18:19]
	ds_write2_b64 v191, v[116:117], v[118:119] offset1:2
	s_nop 7
	v_max_f32_e32 v191, v65, v65
	v_max_f32_e32 v192, v64, v64
	v_max_f32_e32 v191, v192, v191
	v_max3_f32 v192, v66, v67, v49
	v_max3_f32 v191, v191, v48, v50
	v_max3_f32 v191, v191, v51, v68
	v_max3_f32 v192, v192, v70, v71
	v_max3_f32 v191, v191, v69, v52
	v_max3_f32 v192, v192, v54, v55
	v_max3_f32 v191, v191, v53, v72
	v_max3_f32 v192, v192, v74, v75
	v_max3_f32 v191, v191, v73, v56
	v_max3_f32 v192, v192, v58, v59
	v_max3_f32 v191, v191, v57, v76
	v_max3_f32 v192, v192, v78, v79
	v_max3_f32 v191, v191, v77, v60
	v_max3_f32 v192, v192, v62, v63
	v_max3_f32 v191, v191, v61, v192
	v_mov_b32_e32 v192, v191
	s_nop 1
	v_permlane32_swap_b32_e32 v191, v192
	v_max_f32_e32 v191, v191, v192
	v_cmp_lt_f32_e32 vcc, s3, v191
	s_cbranch_vccz .LBB0_747
	v_max_f32_e32 v32, v191, v191
	v_max_f32_e32 v34, 0, v32
	v_exp_f32_e64 v191, -v34
	s_and_saveexec_b64 s[50:51], s[46:47]
	ds_write_b32 v190, v191 offset:45056
	s_or_b64 exec, exec, s[50:51]
	v_add_u32_e32 v47, s16, v166
	ds_read_b128 v[192:195], v47 offset:45120
	ds_read_b128 v[196:199], v47 offset:45152
	ds_read_b128 v[200:203], v47 offset:45056
	ds_read_b128 v[204:207], v47 offset:45088
	v_add_f32_e32 v82, v82, v34
	v_xor_b32_e32 v32, 0x80000000, v82
	v_pk_add_f32 v[64:65], v[64:65], v[34:35] op_sel_hi:[1,0] neg_lo:[0,1] neg_hi:[0,1]
	v_pk_add_f32 v[48:49], v[48:49], v[34:35] op_sel_hi:[1,0] neg_lo:[0,1] neg_hi:[0,1]
	v_pk_add_f32 v[66:67], v[66:67], v[34:35] op_sel_hi:[1,0] neg_lo:[0,1] neg_hi:[0,1]
	v_pk_add_f32 v[50:51], v[50:51], v[34:35] op_sel_hi:[1,0] neg_lo:[0,1] neg_hi:[0,1]
	v_pk_add_f32 v[68:69], v[68:69], v[34:35] op_sel_hi:[1,0] neg_lo:[0,1] neg_hi:[0,1]
	v_pk_add_f32 v[52:53], v[52:53], v[34:35] op_sel_hi:[1,0] neg_lo:[0,1] neg_hi:[0,1]
	v_pk_add_f32 v[70:71], v[70:71], v[34:35] op_sel_hi:[1,0] neg_lo:[0,1] neg_hi:[0,1]
	v_pk_add_f32 v[54:55], v[54:55], v[34:35] op_sel_hi:[1,0] neg_lo:[0,1] neg_hi:[0,1]
	v_pk_add_f32 v[72:73], v[72:73], v[34:35] op_sel_hi:[1,0] neg_lo:[0,1] neg_hi:[0,1]
	v_pk_add_f32 v[56:57], v[56:57], v[34:35] op_sel_hi:[1,0] neg_lo:[0,1] neg_hi:[0,1]
	v_pk_add_f32 v[74:75], v[74:75], v[34:35] op_sel_hi:[1,0] neg_lo:[0,1] neg_hi:[0,1]
	v_pk_add_f32 v[58:59], v[58:59], v[34:35] op_sel_hi:[1,0] neg_lo:[0,1] neg_hi:[0,1]
	v_pk_add_f32 v[76:77], v[76:77], v[34:35] op_sel_hi:[1,0] neg_lo:[0,1] neg_hi:[0,1]
	v_pk_add_f32 v[60:61], v[60:61], v[34:35] op_sel_hi:[1,0] neg_lo:[0,1] neg_hi:[0,1]
	v_pk_add_f32 v[78:79], v[78:79], v[34:35] op_sel_hi:[1,0] neg_lo:[0,1] neg_hi:[0,1]
	v_pk_add_f32 v[62:63], v[62:63], v[34:35] op_sel_hi:[1,0] neg_lo:[0,1] neg_hi:[0,1]
	v_mov_b32_e32 v33, v32
	v_mov_b32_e32 v34, v32
	v_mov_b32_e32 v35, v32
	v_mov_b32_e32 v36, v32
	v_mov_b32_e32 v37, v32
	v_mov_b32_e32 v38, v32
	v_mov_b32_e32 v39, v32
	v_mov_b32_e32 v40, v32
	v_mov_b32_e32 v41, v32
	v_mov_b32_e32 v42, v32
	v_mov_b32_e32 v43, v32
	v_mov_b32_e32 v44, v32
	v_mov_b32_e32 v45, v32
	v_mov_b32_e32 v46, v32
	v_mov_b32_e32 v47, v32
	v_mul_f32_e32 v83, v83, v191
	s_waitcnt lgkmcnt(2)
	v_pk_mul_f32 v[12:13], v[12:13], v[196:197]
	v_pk_mul_f32 v[8:9], v[8:9], v[192:193]
	s_waitcnt lgkmcnt(0)
	v_pk_mul_f32 v[4:5], v[4:5], v[204:205]
	v_pk_mul_f32 v[14:15], v[14:15], v[198:199]
	v_pk_mul_f32 v[10:11], v[10:11], v[194:195]
	v_pk_mul_f32 v[6:7], v[6:7], v[206:207]
	v_pk_mul_f32 v[2:3], v[2:3], v[202:203]
	v_pk_mul_f32 v[0:1], v[0:1], v[200:201]
	v_pk_mul_f32 v[28:29], v[28:29], v[196:197]
	v_pk_mul_f32 v[24:25], v[24:25], v[192:193]
	v_pk_mul_f32 v[20:21], v[20:21], v[204:205]
	v_pk_mul_f32 v[30:31], v[30:31], v[198:199]
	v_pk_mul_f32 v[26:27], v[26:27], v[194:195]
	v_pk_mul_f32 v[22:23], v[22:23], v[206:207]
	v_pk_mul_f32 v[18:19], v[18:19], v[202:203]
	v_pk_mul_f32 v[16:17], v[16:17], v[200:201]

.Latt_end:
	s_cmp_eq_u32 s65, s67
	s_waitcnt lgkmcnt(0)
	s_waitcnt vmcnt(1)
	s_barrier
	s_cbranch_scc0 .LBB0_740
	s_branch .Latt_after
